# GEMM tile preambles: accumulators cleared with v_mov_b64 v[N:N+1], 0 (63 per tile) instead of 127 v_mov_b32 copies, in all 9 GEMM tile loops
# baseline (speedup 1.0000x reference)
; template <class Epi, class Sched, bool ALIGN_EPI = false, bool SP2 = false>
; __device__ __forceinline__ void gemm_phase(PG8_LAS unsigned char* lds, const Gemm g, const Sched& S, const Epi& E) {
;     ...
;         const bool has_next = S.next(ui + 1, nxt);
;         const char* nA = has_next ? (const char*)g.A + (size_t)nxt.pm * tstep : cA; const char* nB = has_next ? (const char*)g.Bt + (size_t)nxt.pn * tstep : cB;
;         for (int t = 0; t < nt; t += 2) {
;             const bool last = (t == nt - 2);
;             const char* a1 = cA + (size_t)(t + 1) * kstep;
;             const char* a2 = last ? nA : cA + (size_t)(t + 2) * kstep; const char* b2 = last ? nB : cB + (size_t)(t + 2) * kstep;
;             const char* a3 = a2 + kstep; const char* b3 = b2 + kstep;
;     ...
; #pragma unroll
;         for (int a = 0; a < 2; ++a)
; #pragma unroll
;             for (int b = 0; b < 2; ++b)
; #pragma unroll
;                 for (int m = 0; m < 4; ++m)
; #pragma unroll
;                     for (int n = 0; n < 2; ++n) acc[a][b][m][n] = (f32x4){0.f, 0.f, 0.f, 0.f};
.LBB0_119:
	s_ashr_i32 s75, s74, 31
	s_lshl_b64 s[28:29], s[74:75], 20
	s_add_u32 s76, s10, s28
	s_addc_u32 s77, s11, s29
	s_and_b64 s[28:29], s[4:5], exec
	s_cselect_b32 s28, s77, s85
	s_cselect_b32 s29, s76, s84
	s_ashr_i32 s73, s72, 31
	s_lshl_b64 s[36:37], s[72:73], 20
	s_add_u32 s78, s6, s36
	s_addc_u32 s79, s7, s37
	s_and_b64 s[36:37], s[4:5], exec
	s_cselect_b32 s73, s79, s87
	s_cselect_b32 s75, s78, s86
	s_add_u32 s84, s84, 0x80080
	s_addc_u32 s85, s85, 0
	s_add_u32 s81, s86, 0x100
	v_mov_b32_e32 v2, 0
	s_addc_u32 s83, s87, 0
	s_mov_b32 s97, -2
	v_mov_b32_e32 v3, v2
	v_mov_b64_e32 v[4:5], 0
	v_mov_b64_e32 v[6:7], 0
	v_mov_b64_e32 v[8:9], 0
	v_mov_b64_e32 v[18:19], 0
	v_mov_b64_e32 v[20:21], 0
	v_mov_b64_e32 v[22:23], 0
	s_waitcnt lgkmcnt(0)
	v_mov_b64_e32 v[24:25], 0
	v_mov_b64_e32 v[34:35], 0
	v_mov_b64_e32 v[36:37], 0
	v_mov_b64_e32 v[38:39], 0
	v_mov_b64_e32 v[40:41], 0
	v_mov_b64_e32 v[50:51], 0
	v_mov_b64_e32 v[52:53], 0
	v_mov_b64_e32 v[54:55], 0
	v_mov_b64_e32 v[56:57], 0
	v_mov_b64_e32 v[10:11], 0
	v_mov_b64_e32 v[12:13], 0
	v_mov_b64_e32 v[14:15], 0
	v_mov_b64_e32 v[16:17], 0
	v_mov_b64_e32 v[26:27], 0
	v_mov_b64_e32 v[28:29], 0
	v_mov_b64_e32 v[30:31], 0
	v_mov_b64_e32 v[32:33], 0
	v_mov_b64_e32 v[42:43], 0
	v_mov_b64_e32 v[44:45], 0
	v_mov_b64_e32 v[46:47], 0
	v_mov_b64_e32 v[48:49], 0
	v_mov_b64_e32 v[58:59], 0
	v_mov_b64_e32 v[60:61], 0
	v_mov_b64_e32 v[62:63], 0
	v_mov_b64_e32 v[64:65], 0
	v_mov_b64_e32 v[66:67], 0
	v_mov_b64_e32 v[68:69], 0
	v_mov_b64_e32 v[70:71], 0
	v_mov_b64_e32 v[72:73], 0
	v_mov_b64_e32 v[82:83], 0
	v_mov_b64_e32 v[84:85], 0
	v_mov_b64_e32 v[86:87], 0
	v_mov_b64_e32 v[88:89], 0
	v_mov_b64_e32 v[98:99], 0
	v_mov_b64_e32 v[100:101], 0
	v_mov_b64_e32 v[102:103], 0
	v_mov_b64_e32 v[104:105], 0
	v_mov_b64_e32 v[114:115], 0
	v_mov_b64_e32 v[116:117], 0
	v_mov_b64_e32 v[118:119], 0
	v_mov_b64_e32 v[120:121], 0
	v_mov_b64_e32 v[74:75], 0
	v_mov_b64_e32 v[76:77], 0
	v_mov_b64_e32 v[78:79], 0
	v_mov_b64_e32 v[80:81], 0
	v_mov_b64_e32 v[90:91], 0
	v_mov_b64_e32 v[92:93], 0
	v_mov_b64_e32 v[94:95], 0
	v_mov_b64_e32 v[96:97], 0
	v_mov_b64_e32 v[106:107], 0
	v_mov_b64_e32 v[108:109], 0
	v_mov_b64_e32 v[110:111], 0
	v_mov_b64_e32 v[112:113], 0
	v_mov_b64_e32 v[122:123], 0
	v_mov_b64_e32 v[124:125], 0
	v_mov_b64_e32 v[126:127], 0
	v_mov_b64_e32 v[128:129], 0

; template <class Epi, class Sched, bool ALIGN_EPI = false, bool SP2 = false>
; __device__ __forceinline__ void gemm_phase(PG8_LAS unsigned char* lds, const Gemm g, const Sched& S, const Epi& E) {
;     ...
;         const bool has_next = S.next(ui + 1, nxt);
;         const char* nA = has_next ? (const char*)g.A + (size_t)nxt.pm * tstep : cA; const char* nB = has_next ? (const char*)g.Bt + (size_t)nxt.pn * tstep : cB;
;         for (int t = 0; t < nt; t += 2) {
;             const bool last = (t == nt - 2);
;             const char* a1 = cA + (size_t)(t + 1) * kstep;
;             const char* a2 = last ? nA : cA + (size_t)(t + 2) * kstep; const char* b2 = last ? nB : cB + (size_t)(t + 2) * kstep;
;             const char* a3 = a2 + kstep; const char* b3 = b2 + kstep;
;     ...
; #pragma unroll
;         for (int a = 0; a < 2; ++a)
; #pragma unroll
;             for (int b = 0; b < 2; ++b)
; #pragma unroll
;                 for (int m = 0; m < 4; ++m)
; #pragma unroll
;                     for (int n = 0; n < 2; ++n) acc[a][b][m][n] = (f32x4){0.f, 0.f, 0.f, 0.f};
.LBB0_197:
	s_ashr_i32 s79, s78, 31
	s_lshl_b64 s[36:37], s[78:79], 18
	s_add_u32 s80, s90, s36
	s_addc_u32 s81, s91, s37
	s_and_b64 s[36:37], s[0:1], exec
	s_cselect_b32 s5, s81, s85
	s_cselect_b32 s7, s80, s84
	s_ashr_i32 s77, s76, 31
	s_lshl_b64 s[36:37], s[76:77], 18
	s_add_u32 s82, s66, s36
	s_addc_u32 s83, s67, s37
	s_and_b64 s[36:37], s[0:1], exec
	s_cselect_b32 s29, s83, s87
	s_cselect_b32 s70, s82, s86
	s_add_u32 s84, s84, 0x20080
	s_addc_u32 s85, s85, 0
	s_add_u32 s77, s86, 0x100
	v_mov_b32_e32 v2, 0
	s_addc_u32 s79, s87, 0
	s_mov_b32 vcc_lo, -2
	v_mov_b32_e32 v3, v2
	v_mov_b64_e32 v[4:5], 0
	v_mov_b64_e32 v[6:7], 0
	v_mov_b64_e32 v[8:9], 0
	v_mov_b64_e32 v[18:19], 0
	v_mov_b64_e32 v[20:21], 0
	v_mov_b64_e32 v[22:23], 0
	s_waitcnt lgkmcnt(0)
	v_mov_b64_e32 v[24:25], 0
	v_mov_b64_e32 v[34:35], 0
	v_mov_b64_e32 v[36:37], 0
	v_mov_b64_e32 v[38:39], 0
	v_mov_b64_e32 v[40:41], 0
	v_mov_b64_e32 v[50:51], 0
	v_mov_b64_e32 v[52:53], 0
	v_mov_b64_e32 v[54:55], 0
	v_mov_b64_e32 v[56:57], 0
	v_mov_b64_e32 v[10:11], 0
	v_mov_b64_e32 v[12:13], 0
	v_mov_b64_e32 v[14:15], 0
	v_mov_b64_e32 v[16:17], 0
	v_mov_b64_e32 v[26:27], 0
	v_mov_b64_e32 v[28:29], 0
	v_mov_b64_e32 v[30:31], 0
	v_mov_b64_e32 v[32:33], 0
	v_mov_b64_e32 v[42:43], 0
	v_mov_b64_e32 v[44:45], 0
	v_mov_b64_e32 v[46:47], 0
	v_mov_b64_e32 v[48:49], 0
	v_mov_b64_e32 v[58:59], 0
	v_mov_b64_e32 v[60:61], 0
	v_mov_b64_e32 v[62:63], 0
	v_mov_b64_e32 v[64:65], 0
	v_mov_b64_e32 v[66:67], 0
	v_mov_b64_e32 v[68:69], 0
	v_mov_b64_e32 v[70:71], 0
	v_mov_b64_e32 v[72:73], 0
	v_mov_b64_e32 v[82:83], 0
	v_mov_b64_e32 v[84:85], 0
	v_mov_b64_e32 v[86:87], 0
	v_mov_b64_e32 v[88:89], 0
	v_mov_b64_e32 v[98:99], 0
	v_mov_b64_e32 v[100:101], 0
	v_mov_b64_e32 v[102:103], 0
	v_mov_b64_e32 v[104:105], 0
	v_mov_b64_e32 v[114:115], 0
	v_mov_b64_e32 v[116:117], 0
	v_mov_b64_e32 v[118:119], 0
	v_mov_b64_e32 v[120:121], 0
	v_mov_b64_e32 v[74:75], 0
	v_mov_b64_e32 v[76:77], 0
	v_mov_b64_e32 v[78:79], 0
	v_mov_b64_e32 v[80:81], 0
	v_mov_b64_e32 v[90:91], 0
	v_mov_b64_e32 v[92:93], 0
	v_mov_b64_e32 v[94:95], 0
	v_mov_b64_e32 v[96:97], 0
	v_mov_b64_e32 v[106:107], 0
	v_mov_b64_e32 v[108:109], 0
	v_mov_b64_e32 v[110:111], 0
	v_mov_b64_e32 v[112:113], 0
	v_mov_b64_e32 v[122:123], 0
	v_mov_b64_e32 v[124:125], 0
	v_mov_b64_e32 v[126:127], 0
	v_mov_b64_e32 v[128:129], 0

; template <class Epi, class Sched, bool ALIGN_EPI = false, bool SP2 = false>
; __device__ __forceinline__ void gemm_phase(PG8_LAS unsigned char* lds, const Gemm g, const Sched& S, const Epi& E) {
;     ...
;         const bool has_next = S.next(ui + 1, nxt);
;         const char* nA = has_next ? (const char*)g.A + (size_t)nxt.pm * tstep : cA; const char* nB = has_next ? (const char*)g.Bt + (size_t)nxt.pn * tstep : cB;
;         for (int t = 0; t < nt; t += 2) {
;             const bool last = (t == nt - 2);
;             const char* a1 = cA + (size_t)(t + 1) * kstep;
;             const char* a2 = last ? nA : cA + (size_t)(t + 2) * kstep; const char* b2 = last ? nB : cB + (size_t)(t + 2) * kstep;
;             const char* a3 = a2 + kstep; const char* b3 = b2 + kstep;
;     ...
; #pragma unroll
;         for (int a = 0; a < 2; ++a)
; #pragma unroll
;             for (int b = 0; b < 2; ++b)
; #pragma unroll
;                 for (int m = 0; m < 4; ++m)
; #pragma unroll
;                     for (int n = 0; n < 2; ++n) acc[a][b][m][n] = (f32x4){0.f, 0.f, 0.f, 0.f};
.LBB0_277:
	s_ashr_i32 s71, s70, 31
	s_lshl_b64 s[28:29], s[70:71], 17
	s_add_u32 s72, s95, s28
	s_addc_u32 s73, s96, s29
	s_and_b64 s[28:29], s[0:1], exec
	s_cselect_b32 s17, s73, s79
	s_cselect_b32 s28, s72, s78
	s_ashr_i32 s69, s68, 31
	s_lshl_b64 s[36:37], s[68:69], 17
	s_add_u32 s74, s64, s36
	s_addc_u32 s75, s65, s37
	s_and_b64 s[36:37], s[0:1], exec
	v_mov_b32_e32 v2, 0
	s_cselect_b32 s29, s75, s77
	s_cselect_b32 s48, s74, s76
	s_mov_b32 s69, 0
	s_mov_b64 s[80:81], -1
	s_mov_b64 s[82:83], 0
	v_mov_b32_e32 v3, v2
	v_mov_b64_e32 v[4:5], 0
	v_mov_b64_e32 v[6:7], 0
	v_mov_b64_e32 v[8:9], 0
	v_mov_b64_e32 v[18:19], 0
	v_mov_b64_e32 v[20:21], 0
	v_mov_b64_e32 v[22:23], 0
	s_waitcnt lgkmcnt(0)
	v_mov_b64_e32 v[24:25], 0
	v_mov_b64_e32 v[34:35], 0
	v_mov_b64_e32 v[36:37], 0
	v_mov_b64_e32 v[38:39], 0
	v_mov_b64_e32 v[40:41], 0
	v_mov_b64_e32 v[50:51], 0
	v_mov_b64_e32 v[52:53], 0
	v_mov_b64_e32 v[54:55], 0
	v_mov_b64_e32 v[56:57], 0
	v_mov_b64_e32 v[10:11], 0
	v_mov_b64_e32 v[12:13], 0
	v_mov_b64_e32 v[14:15], 0
	v_mov_b64_e32 v[16:17], 0
	v_mov_b64_e32 v[26:27], 0
	v_mov_b64_e32 v[28:29], 0
	v_mov_b64_e32 v[30:31], 0
	v_mov_b64_e32 v[32:33], 0
	v_mov_b64_e32 v[42:43], 0
	v_mov_b64_e32 v[44:45], 0
	v_mov_b64_e32 v[46:47], 0
	v_mov_b64_e32 v[48:49], 0
	v_mov_b64_e32 v[58:59], 0
	v_mov_b64_e32 v[60:61], 0
	v_mov_b64_e32 v[62:63], 0
	v_mov_b64_e32 v[64:65], 0
	v_mov_b64_e32 v[66:67], 0
	v_mov_b64_e32 v[68:69], 0
	v_mov_b64_e32 v[70:71], 0
	v_mov_b64_e32 v[72:73], 0
	v_mov_b64_e32 v[82:83], 0
	v_mov_b64_e32 v[84:85], 0
	v_mov_b64_e32 v[86:87], 0
	v_mov_b64_e32 v[88:89], 0
	v_mov_b64_e32 v[98:99], 0
	v_mov_b64_e32 v[100:101], 0
	v_mov_b64_e32 v[102:103], 0
	v_mov_b64_e32 v[104:105], 0
	v_mov_b64_e32 v[114:115], 0
	v_mov_b64_e32 v[116:117], 0
	v_mov_b64_e32 v[118:119], 0
	v_mov_b64_e32 v[120:121], 0
	v_mov_b64_e32 v[74:75], 0
	v_mov_b64_e32 v[76:77], 0
	v_mov_b64_e32 v[78:79], 0
	v_mov_b64_e32 v[80:81], 0
	v_mov_b64_e32 v[90:91], 0
	v_mov_b64_e32 v[92:93], 0
	v_mov_b64_e32 v[94:95], 0
	v_mov_b64_e32 v[96:97], 0
	v_mov_b64_e32 v[106:107], 0
	v_mov_b64_e32 v[108:109], 0
	v_mov_b64_e32 v[110:111], 0
	v_mov_b64_e32 v[112:113], 0
	v_mov_b64_e32 v[122:123], 0
	v_mov_b64_e32 v[124:125], 0
	v_mov_b64_e32 v[126:127], 0
	v_mov_b64_e32 v[128:129], 0

; template <class Epi, class Sched, bool ALIGN_EPI = false, bool SP2 = false>
; __device__ __forceinline__ void gemm_phase(PG8_LAS unsigned char* lds, const Gemm g, const Sched& S, const Epi& E) {
;     ...
;         const bool has_next = S.next(ui + 1, nxt);
;         const char* nA = has_next ? (const char*)g.A + (size_t)nxt.pm * tstep : cA; const char* nB = has_next ? (const char*)g.Bt + (size_t)nxt.pn * tstep : cB;
;         for (int t = 0; t < nt; t += 2) {
;             const bool last = (t == nt - 2);
;             const char* a1 = cA + (size_t)(t + 1) * kstep;
;             const char* a2 = last ? nA : cA + (size_t)(t + 2) * kstep; const char* b2 = last ? nB : cB + (size_t)(t + 2) * kstep;
;             const char* a3 = a2 + kstep; const char* b3 = b2 + kstep;
;     ...
; #pragma unroll
;         for (int a = 0; a < 2; ++a)
; #pragma unroll
;             for (int b = 0; b < 2; ++b)
; #pragma unroll
;                 for (int m = 0; m < 4; ++m)
; #pragma unroll
;                     for (int n = 0; n < 2; ++n) acc[a][b][m][n] = (f32x4){0.f, 0.f, 0.f, 0.f};
.LBB0_715:
	s_ashr_i32 s47, s46, 31
	s_lshl_b64 s[48:49], s[46:47], 20
	s_add_u32 s48, s10, s48
	s_addc_u32 s49, s11, s49
	s_and_b64 s[50:51], s[0:1], exec
	s_cselect_b32 s47, s49, s67
	s_cselect_b32 s74, s48, s66
	s_ashr_i32 s45, s44, 31
	s_lshl_b64 s[50:51], s[44:45], 20
	s_add_u32 s50, s8, s50
	s_addc_u32 s51, s9, s51
	s_and_b64 s[70:71], s[0:1], exec
	s_cselect_b32 s45, s51, s69
	s_cselect_b32 s75, s50, s68
	s_add_u32 s66, s66, 0x80080
	s_addc_u32 s67, s67, 0
	s_add_u32 s76, s68, 0x100
	v_mov_b32_e32 v2, 0
	s_addc_u32 s77, s69, 0
	s_mov_b32 s78, -2
	v_mov_b32_e32 v3, v2
	v_mov_b64_e32 v[4:5], 0
	v_mov_b64_e32 v[6:7], 0
	v_mov_b64_e32 v[8:9], 0
	v_mov_b64_e32 v[18:19], 0
	v_mov_b64_e32 v[20:21], 0
	v_mov_b64_e32 v[22:23], 0
	s_waitcnt lgkmcnt(0)
	v_mov_b64_e32 v[24:25], 0
	v_mov_b64_e32 v[34:35], 0
	v_mov_b64_e32 v[36:37], 0
	v_mov_b64_e32 v[38:39], 0
	v_mov_b64_e32 v[40:41], 0
	v_mov_b64_e32 v[50:51], 0
	v_mov_b64_e32 v[52:53], 0
	v_mov_b64_e32 v[54:55], 0
	v_mov_b64_e32 v[56:57], 0
	v_mov_b64_e32 v[10:11], 0
	v_mov_b64_e32 v[12:13], 0
	v_mov_b64_e32 v[14:15], 0
	v_mov_b64_e32 v[16:17], 0
	v_mov_b64_e32 v[26:27], 0
	v_mov_b64_e32 v[28:29], 0
	v_mov_b64_e32 v[30:31], 0
	v_mov_b64_e32 v[32:33], 0
	v_mov_b64_e32 v[42:43], 0
	v_mov_b64_e32 v[44:45], 0
	v_mov_b64_e32 v[46:47], 0
	v_mov_b64_e32 v[48:49], 0
	v_mov_b64_e32 v[58:59], 0
	v_mov_b64_e32 v[60:61], 0
	v_mov_b64_e32 v[62:63], 0
	v_mov_b64_e32 v[64:65], 0
	v_mov_b64_e32 v[66:67], 0
	v_mov_b64_e32 v[68:69], 0
	v_mov_b64_e32 v[70:71], 0
	v_mov_b64_e32 v[72:73], 0
	v_mov_b64_e32 v[82:83], 0
	v_mov_b64_e32 v[84:85], 0
	v_mov_b64_e32 v[86:87], 0
	v_mov_b64_e32 v[88:89], 0
	v_mov_b64_e32 v[98:99], 0
	v_mov_b64_e32 v[100:101], 0
	v_mov_b64_e32 v[102:103], 0
	v_mov_b64_e32 v[104:105], 0
	v_mov_b64_e32 v[114:115], 0
	v_mov_b64_e32 v[116:117], 0
	v_mov_b64_e32 v[118:119], 0
	v_mov_b64_e32 v[120:121], 0
	v_mov_b64_e32 v[74:75], 0
	v_mov_b64_e32 v[76:77], 0
	v_mov_b64_e32 v[78:79], 0
	v_mov_b64_e32 v[80:81], 0
	v_mov_b64_e32 v[90:91], 0
	v_mov_b64_e32 v[92:93], 0
	v_mov_b64_e32 v[94:95], 0
	v_mov_b64_e32 v[96:97], 0
	v_mov_b64_e32 v[106:107], 0
	v_mov_b64_e32 v[108:109], 0
	v_mov_b64_e32 v[110:111], 0
	v_mov_b64_e32 v[112:113], 0
	v_mov_b64_e32 v[122:123], 0
	v_mov_b64_e32 v[124:125], 0
	v_mov_b64_e32 v[126:127], 0
	v_mov_b64_e32 v[128:129], 0

; template <class Epi, class Sched, bool ALIGN_EPI = false, bool SP2 = false>
; __device__ __forceinline__ void gemm_phase(PG8_LAS unsigned char* lds, const Gemm g, const Sched& S, const Epi& E) {
;     ...
;         const bool has_next = S.next(ui + 1, nxt);
;         const char* nA = has_next ? (const char*)g.A + (size_t)nxt.pm * tstep : cA; const char* nB = has_next ? (const char*)g.Bt + (size_t)nxt.pn * tstep : cB;
;         for (int t = 0; t < nt; t += 2) {
;             const bool last = (t == nt - 2);
;             const char* a1 = cA + (size_t)(t + 1) * kstep;
;             const char* a2 = last ? nA : cA + (size_t)(t + 2) * kstep; const char* b2 = last ? nB : cB + (size_t)(t + 2) * kstep;
;             const char* a3 = a2 + kstep; const char* b3 = b2 + kstep;
;     ...
; #pragma unroll
;         for (int a = 0; a < 2; ++a)
; #pragma unroll
;             for (int b = 0; b < 2; ++b)
; #pragma unroll
;                 for (int m = 0; m < 4; ++m)
; #pragma unroll
;                     for (int n = 0; n < 2; ++n) acc[a][b][m][n] = (f32x4){0.f, 0.f, 0.f, 0.f};
.LBB0_756:
	s_ashr_i32 s45, s44, 31
	s_lshl_b64 s[46:47], s[44:45], 20
	s_add_u32 s46, s22, s46
	s_addc_u32 s47, s23, s47
	s_and_b64 s[48:49], s[0:1], exec
	s_cselect_b32 s45, s47, s65
	s_cselect_b32 s61, s46, s64
	s_ashr_i32 s43, s42, 31
	s_lshl_b64 s[48:49], s[42:43], 20
	v_readlane_b32 s43, v253, 16
	s_add_u32 s48, s43, s48
	v_readlane_b32 s43, v253, 17
	s_addc_u32 s49, s43, s49
	s_and_b64 s[62:63], s[0:1], exec
	s_cselect_b32 s43, s49, s67
	s_cselect_b32 s62, s48, s66
	s_add_u32 s64, s64, 0x80080
	s_addc_u32 s65, s65, 0
	s_add_u32 s63, s66, 0x100
	v_mov_b32_e32 v2, 0
	s_addc_u32 s70, s67, 0
	s_mov_b32 s71, -2
	v_mov_b32_e32 v3, v2
	v_mov_b64_e32 v[4:5], 0
	v_mov_b64_e32 v[6:7], 0
	v_mov_b64_e32 v[8:9], 0
	v_mov_b64_e32 v[18:19], 0
	v_mov_b64_e32 v[20:21], 0
	v_mov_b64_e32 v[22:23], 0
	s_waitcnt lgkmcnt(0)
	v_mov_b64_e32 v[24:25], 0
	v_mov_b64_e32 v[34:35], 0
	v_mov_b64_e32 v[36:37], 0
	v_mov_b64_e32 v[38:39], 0
	v_mov_b64_e32 v[40:41], 0
	v_mov_b64_e32 v[50:51], 0
	v_mov_b64_e32 v[52:53], 0
	v_mov_b64_e32 v[54:55], 0
	v_mov_b64_e32 v[56:57], 0
	v_mov_b64_e32 v[10:11], 0
	v_mov_b64_e32 v[12:13], 0
	v_mov_b64_e32 v[14:15], 0
	v_mov_b64_e32 v[16:17], 0
	v_mov_b64_e32 v[26:27], 0
	v_mov_b64_e32 v[28:29], 0
	v_mov_b64_e32 v[30:31], 0
	v_mov_b64_e32 v[32:33], 0
	v_mov_b64_e32 v[42:43], 0
	v_mov_b64_e32 v[44:45], 0
	v_mov_b64_e32 v[46:47], 0
	v_mov_b64_e32 v[48:49], 0
	v_mov_b64_e32 v[58:59], 0
	v_mov_b64_e32 v[60:61], 0
	v_mov_b64_e32 v[62:63], 0
	v_mov_b64_e32 v[64:65], 0
	v_mov_b64_e32 v[66:67], 0
	v_mov_b64_e32 v[68:69], 0
	v_mov_b64_e32 v[70:71], 0
	v_mov_b64_e32 v[72:73], 0
	s_waitcnt vmcnt(0)
	v_mov_b64_e32 v[82:83], 0
	v_mov_b64_e32 v[84:85], 0
	v_mov_b64_e32 v[86:87], 0
	v_mov_b64_e32 v[88:89], 0
	v_mov_b64_e32 v[98:99], 0
	v_mov_b64_e32 v[100:101], 0
	v_mov_b64_e32 v[102:103], 0
	v_mov_b64_e32 v[104:105], 0
	v_mov_b64_e32 v[114:115], 0
	v_mov_b64_e32 v[116:117], 0
	v_mov_b64_e32 v[118:119], 0
	v_mov_b64_e32 v[120:121], 0
	v_mov_b64_e32 v[74:75], 0
	v_mov_b64_e32 v[76:77], 0
	v_mov_b64_e32 v[78:79], 0
	v_mov_b64_e32 v[80:81], 0
	v_mov_b64_e32 v[90:91], 0
	v_mov_b64_e32 v[92:93], 0
	v_mov_b64_e32 v[94:95], 0
	v_mov_b64_e32 v[96:97], 0
	v_mov_b64_e32 v[106:107], 0
	v_mov_b64_e32 v[108:109], 0
	v_mov_b64_e32 v[110:111], 0
	v_mov_b64_e32 v[112:113], 0
	v_mov_b64_e32 v[122:123], 0
	v_mov_b64_e32 v[124:125], 0
	v_mov_b64_e32 v[126:127], 0
	v_mov_b64_e32 v[128:129], 0

; template <class Epi, class Sched, bool ALIGN_EPI = false, bool SP2 = false>
; __device__ __forceinline__ void gemm_phase(PG8_LAS unsigned char* lds, const Gemm g, const Sched& S, const Epi& E) {
;     ...
;         const bool has_next = S.next(ui + 1, nxt);
;         const char* nA = has_next ? (const char*)g.A + (size_t)nxt.pm * tstep : cA; const char* nB = has_next ? (const char*)g.Bt + (size_t)nxt.pn * tstep : cB;
;         for (int t = 0; t < nt; t += 2) {
;             const bool last = (t == nt - 2);
;             const char* a1 = cA + (size_t)(t + 1) * kstep;
;             const char* a2 = last ? nA : cA + (size_t)(t + 2) * kstep; const char* b2 = last ? nB : cB + (size_t)(t + 2) * kstep;
;             const char* a3 = a2 + kstep; const char* b3 = b2 + kstep;
;     ...
; #pragma unroll
;         for (int a = 0; a < 2; ++a)
; #pragma unroll
;             for (int b = 0; b < 2; ++b)
; #pragma unroll
;                 for (int m = 0; m < 4; ++m)
; #pragma unroll
;                     for (int n = 0; n < 2; ++n) acc[a][b][m][n] = (f32x4){0.f, 0.f, 0.f, 0.f};
.LBB0_780:
	s_ashr_i32 s43, s42, 31
	s_lshl_b64 s[44:45], s[42:43], 20
	s_add_u32 s44, s18, s44
	s_addc_u32 s45, s19, s45
	s_and_b64 s[46:47], s[0:1], exec
	s_cselect_b32 s43, s45, s51
	s_cselect_b32 s61, s44, s50
	s_ashr_i32 s41, s40, 31
	s_lshl_b64 s[46:47], s[40:41], 20
	v_readlane_b32 s41, v253, 18
	s_add_u32 s46, s41, s46
	v_readlane_b32 s41, v253, 19
	s_addc_u32 s47, s41, s47
	s_and_b64 s[62:63], s[0:1], exec
	s_cselect_b32 s41, s47, s65
	s_cselect_b32 s62, s46, s64
	s_add_u32 s50, s50, 0x80080
	s_addc_u32 s51, s51, 0
	s_add_u32 s63, s64, 0x100
	v_mov_b32_e32 v2, 0
	s_addc_u32 s68, s65, 0
	s_mov_b32 s69, -2
	v_mov_b32_e32 v3, v2
	v_mov_b64_e32 v[4:5], 0
	v_mov_b64_e32 v[6:7], 0
	v_mov_b64_e32 v[8:9], 0
	v_mov_b64_e32 v[18:19], 0
	v_mov_b64_e32 v[20:21], 0
	v_mov_b64_e32 v[22:23], 0
	s_waitcnt lgkmcnt(0)
	v_mov_b64_e32 v[24:25], 0
	v_mov_b64_e32 v[34:35], 0
	v_mov_b64_e32 v[36:37], 0
	v_mov_b64_e32 v[38:39], 0
	v_mov_b64_e32 v[40:41], 0
	v_mov_b64_e32 v[50:51], 0
	v_mov_b64_e32 v[52:53], 0
	v_mov_b64_e32 v[54:55], 0
	v_mov_b64_e32 v[56:57], 0
	v_mov_b64_e32 v[10:11], 0
	v_mov_b64_e32 v[12:13], 0
	v_mov_b64_e32 v[14:15], 0
	v_mov_b64_e32 v[16:17], 0
	v_mov_b64_e32 v[26:27], 0
	v_mov_b64_e32 v[28:29], 0
	v_mov_b64_e32 v[30:31], 0
	v_mov_b64_e32 v[32:33], 0
	v_mov_b64_e32 v[42:43], 0
	v_mov_b64_e32 v[44:45], 0
	v_mov_b64_e32 v[46:47], 0
	v_mov_b64_e32 v[48:49], 0
	v_mov_b64_e32 v[58:59], 0
	v_mov_b64_e32 v[60:61], 0
	v_mov_b64_e32 v[62:63], 0
	v_mov_b64_e32 v[64:65], 0
	v_mov_b64_e32 v[66:67], 0
	v_mov_b64_e32 v[68:69], 0
	v_mov_b64_e32 v[70:71], 0
	v_mov_b64_e32 v[72:73], 0
	s_waitcnt vmcnt(0)
	v_mov_b64_e32 v[82:83], 0
	v_mov_b64_e32 v[84:85], 0
	v_mov_b64_e32 v[86:87], 0
	v_mov_b64_e32 v[88:89], 0
	v_mov_b64_e32 v[98:99], 0
	v_mov_b64_e32 v[100:101], 0
	v_mov_b64_e32 v[102:103], 0
	v_mov_b64_e32 v[104:105], 0
	v_mov_b64_e32 v[114:115], 0
	v_mov_b64_e32 v[116:117], 0
	v_mov_b64_e32 v[118:119], 0
	v_mov_b64_e32 v[120:121], 0
	v_mov_b64_e32 v[74:75], 0
	v_mov_b64_e32 v[76:77], 0
	v_mov_b64_e32 v[78:79], 0
	v_mov_b64_e32 v[80:81], 0
	v_mov_b64_e32 v[90:91], 0
	v_mov_b64_e32 v[92:93], 0
	v_mov_b64_e32 v[94:95], 0
	v_mov_b64_e32 v[96:97], 0
	v_mov_b64_e32 v[106:107], 0
	v_mov_b64_e32 v[108:109], 0
	v_mov_b64_e32 v[110:111], 0
	v_mov_b64_e32 v[112:113], 0
	v_mov_b64_e32 v[122:123], 0
	v_mov_b64_e32 v[124:125], 0
	v_mov_b64_e32 v[126:127], 0
	v_mov_b64_e32 v[128:129], 0

; template <class Epi, class Sched, bool ALIGN_EPI = false, bool SP2 = false>
; __device__ __forceinline__ void gemm_phase(PG8_LAS unsigned char* lds, const Gemm g, const Sched& S, const Epi& E) {
;     ...
;         const bool has_next = S.next(ui + 1, nxt);
;         const char* nA = has_next ? (const char*)g.A + (size_t)nxt.pm * tstep : cA; const char* nB = has_next ? (const char*)g.Bt + (size_t)nxt.pn * tstep : cB;
;         for (int t = 0; t < nt; t += 2) {
;             const bool last = (t == nt - 2);
;             const char* a1 = cA + (size_t)(t + 1) * kstep;
;             const char* a2 = last ? nA : cA + (size_t)(t + 2) * kstep; const char* b2 = last ? nB : cB + (size_t)(t + 2) * kstep;
;             const char* a3 = a2 + kstep; const char* b3 = b2 + kstep;
;     ...
; #pragma unroll
;         for (int a = 0; a < 2; ++a)
; #pragma unroll
;             for (int b = 0; b < 2; ++b)
; #pragma unroll
;                 for (int m = 0; m < 4; ++m)
; #pragma unroll
;                     for (int n = 0; n < 2; ++n) acc[a][b][m][n] = (f32x4){0.f, 0.f, 0.f, 0.f};
.LBB0_823:
	s_ashr_i32 s43, s42, 31
	s_lshl_b64 s[44:45], s[42:43], 20
	s_add_u32 s44, s6, s44
	s_addc_u32 s45, s7, s45
	s_and_b64 s[46:47], s[4:5], exec
	s_cselect_b32 s43, s45, s51
	s_cselect_b32 s49, s44, s50
	s_ashr_i32 s41, s40, 31
	s_lshl_b64 s[46:47], s[40:41], 20
	v_readlane_b32 s41, v253, 20
	s_add_u32 s46, s41, s46
	v_readlane_b32 s41, v253, 21
	s_addc_u32 s47, s41, s47
	s_and_b64 s[62:63], s[4:5], exec
	s_cselect_b32 s41, s47, s65
	s_cselect_b32 s62, s46, s64
	s_add_u32 s50, s50, 0x80080
	s_addc_u32 s51, s51, 0
	s_add_u32 s63, s64, 0x100
	v_mov_b32_e32 v2, 0
	s_addc_u32 s68, s65, 0
	s_mov_b32 s69, -2
	v_mov_b32_e32 v3, v2
	v_mov_b64_e32 v[4:5], 0
	v_mov_b64_e32 v[6:7], 0
	v_mov_b64_e32 v[8:9], 0
	v_mov_b64_e32 v[18:19], 0
	v_mov_b64_e32 v[20:21], 0
	v_mov_b64_e32 v[22:23], 0
	s_waitcnt lgkmcnt(0)
	v_mov_b64_e32 v[24:25], 0
	v_mov_b64_e32 v[34:35], 0
	v_mov_b64_e32 v[36:37], 0
	v_mov_b64_e32 v[38:39], 0
	v_mov_b64_e32 v[40:41], 0
	v_mov_b64_e32 v[50:51], 0
	v_mov_b64_e32 v[52:53], 0
	v_mov_b64_e32 v[54:55], 0
	v_mov_b64_e32 v[56:57], 0
	v_mov_b64_e32 v[10:11], 0
	v_mov_b64_e32 v[12:13], 0
	v_mov_b64_e32 v[14:15], 0
	v_mov_b64_e32 v[16:17], 0
	v_mov_b64_e32 v[26:27], 0
	v_mov_b64_e32 v[28:29], 0
	v_mov_b64_e32 v[30:31], 0
	v_mov_b64_e32 v[32:33], 0
	v_mov_b64_e32 v[42:43], 0
	v_mov_b64_e32 v[44:45], 0
	v_mov_b64_e32 v[46:47], 0
	v_mov_b64_e32 v[48:49], 0
	v_mov_b64_e32 v[58:59], 0
	v_mov_b64_e32 v[60:61], 0
	v_mov_b64_e32 v[62:63], 0
	v_mov_b64_e32 v[64:65], 0
	v_mov_b64_e32 v[66:67], 0
	v_mov_b64_e32 v[68:69], 0
	v_mov_b64_e32 v[70:71], 0
	v_mov_b64_e32 v[72:73], 0
	v_mov_b64_e32 v[82:83], 0
	v_mov_b64_e32 v[84:85], 0
	v_mov_b64_e32 v[86:87], 0
	v_mov_b64_e32 v[88:89], 0
	v_mov_b64_e32 v[98:99], 0
	v_mov_b64_e32 v[100:101], 0
	v_mov_b64_e32 v[102:103], 0
	v_mov_b64_e32 v[104:105], 0
	v_mov_b64_e32 v[114:115], 0
	v_mov_b64_e32 v[116:117], 0
	v_mov_b64_e32 v[118:119], 0
	v_mov_b64_e32 v[120:121], 0
	v_mov_b64_e32 v[74:75], 0
	v_mov_b64_e32 v[76:77], 0
	v_mov_b64_e32 v[78:79], 0
	v_mov_b64_e32 v[80:81], 0
	v_mov_b64_e32 v[90:91], 0
	v_mov_b64_e32 v[92:93], 0
	v_mov_b64_e32 v[94:95], 0
	v_mov_b64_e32 v[96:97], 0
	v_mov_b64_e32 v[106:107], 0
	v_mov_b64_e32 v[108:109], 0
	v_mov_b64_e32 v[110:111], 0
	v_mov_b64_e32 v[112:113], 0
	v_mov_b64_e32 v[122:123], 0
	v_mov_b64_e32 v[124:125], 0
	v_mov_b64_e32 v[126:127], 0
	v_mov_b64_e32 v[128:129], 0

; template <class Epi, class Sched, bool ALIGN_EPI = false, bool SP2 = false>
; __device__ __forceinline__ void gemm_phase(PG8_LAS unsigned char* lds, const Gemm g, const Sched& S, const Epi& E) {
;     ...
;         const bool has_next = S.next(ui + 1, nxt);
;         const char* nA = has_next ? (const char*)g.A + (size_t)nxt.pm * tstep : cA; const char* nB = has_next ? (const char*)g.Bt + (size_t)nxt.pn * tstep : cB;
;         for (int t = 0; t < nt; t += 2) {
;             const bool last = (t == nt - 2);
;             const char* a1 = cA + (size_t)(t + 1) * kstep;
;             const char* a2 = last ? nA : cA + (size_t)(t + 2) * kstep; const char* b2 = last ? nB : cB + (size_t)(t + 2) * kstep;
;             const char* a3 = a2 + kstep; const char* b3 = b2 + kstep;
;     ...
; #pragma unroll
;         for (int a = 0; a < 2; ++a)
; #pragma unroll
;             for (int b = 0; b < 2; ++b)
; #pragma unroll
;                 for (int m = 0; m < 4; ++m)
; #pragma unroll
;                     for (int n = 0; n < 2; ++n) acc[a][b][m][n] = (f32x4){0.f, 0.f, 0.f, 0.f};
.LBB0_907:
	s_ashr_i32 s49, s48, 31
	s_lshl_b64 s[50:51], s[48:49], 20
	s_add_u32 s50, s12, s50
	s_addc_u32 s51, s13, s51
	s_and_b64 s[64:65], s[6:7], exec
	s_cselect_b32 s49, s51, s69
	s_cselect_b32 s82, s50, s68
	s_ashr_i32 s47, s46, 31
	s_lshl_b64 s[64:65], s[46:47], 20
	v_readlane_b32 s72, v253, 22
	v_readlane_b32 s73, v253, 23
	s_add_u32 s64, s72, s64
	s_addc_u32 s65, s73, s65
	s_and_b64 s[72:73], s[6:7], exec
	s_cselect_b32 s47, s65, s71
	s_cselect_b32 s83, s64, s70
	s_add_u32 s68, s68, 0x80080
	s_addc_u32 s69, s69, 0
	s_add_u32 s84, s70, 0x100
	v_mov_b32_e32 v2, 0
	s_addc_u32 s85, s71, 0
	s_mov_b32 s86, -2
	v_mov_b32_e32 v3, v2
	v_mov_b64_e32 v[4:5], 0
	v_mov_b64_e32 v[14:15], 0
	v_mov_b64_e32 v[16:17], 0
	v_mov_b64_e32 v[18:19], 0
	v_mov_b64_e32 v[20:21], 0
	v_mov_b64_e32 v[22:23], 0
	s_waitcnt lgkmcnt(0)
	v_mov_b64_e32 v[24:25], 0
	v_mov_b64_e32 v[34:35], 0
	v_mov_b64_e32 v[36:37], 0
	v_mov_b64_e32 v[38:39], 0
	v_mov_b64_e32 v[40:41], 0
	v_mov_b64_e32 v[50:51], 0
	v_mov_b64_e32 v[52:53], 0
	v_mov_b64_e32 v[54:55], 0
	v_mov_b64_e32 v[56:57], 0
	v_mov_b64_e32 v[6:7], 0
	v_mov_b64_e32 v[8:9], 0
	v_mov_b64_e32 v[10:11], 0
	v_mov_b64_e32 v[12:13], 0
	v_mov_b64_e32 v[26:27], 0
	v_mov_b64_e32 v[28:29], 0
	v_mov_b64_e32 v[30:31], 0
	v_mov_b64_e32 v[32:33], 0
	v_mov_b64_e32 v[42:43], 0
	v_mov_b64_e32 v[44:45], 0
	v_mov_b64_e32 v[46:47], 0
	v_mov_b64_e32 v[48:49], 0
	v_mov_b64_e32 v[58:59], 0
	v_mov_b64_e32 v[60:61], 0
	v_mov_b64_e32 v[62:63], 0
	v_mov_b64_e32 v[64:65], 0
	v_mov_b64_e32 v[66:67], 0
	v_mov_b64_e32 v[68:69], 0
	v_mov_b64_e32 v[74:75], 0
	v_mov_b64_e32 v[76:77], 0
	v_mov_b64_e32 v[114:115], 0
	v_mov_b64_e32 v[116:117], 0
	v_mov_b64_e32 v[118:119], 0
	v_mov_b64_e32 v[120:121], 0
	v_mov_b64_e32 v[130:131], 0
	v_mov_b64_e32 v[132:133], 0
	v_mov_b64_e32 v[134:135], 0
	v_mov_b64_e32 v[136:137], 0
	v_mov_b64_e32 v[146:147], 0
	v_mov_b64_e32 v[148:149], 0
	v_mov_b64_e32 v[150:151], 0
	v_mov_b64_e32 v[152:153], 0
	v_mov_b64_e32 v[70:71], 0
	v_mov_b64_e32 v[72:73], 0
	v_mov_b64_e32 v[78:79], 0
	v_mov_b64_e32 v[80:81], 0
	v_mov_b64_e32 v[122:123], 0
	v_mov_b64_e32 v[124:125], 0
	v_mov_b64_e32 v[126:127], 0
	v_mov_b64_e32 v[128:129], 0
	v_mov_b64_e32 v[138:139], 0
	v_mov_b64_e32 v[140:141], 0
	v_mov_b64_e32 v[142:143], 0
	v_mov_b64_e32 v[144:145], 0
	v_mov_b64_e32 v[154:155], 0
	v_mov_b64_e32 v[156:157], 0
	v_mov_b64_e32 v[158:159], 0
	v_mov_b64_e32 v[160:161], 0
	s_waitcnt vmcnt(0)

; template <class Epi, class Sched, bool ALIGN_EPI = false, bool SP2 = false>
; __device__ __forceinline__ void gemm_phase(PG8_LAS unsigned char* lds, const Gemm g, const Sched& S, const Epi& E) {
;     ...
;         const bool has_next = S.next(ui + 1, nxt);
;         const char* nA = has_next ? (const char*)g.A + (size_t)nxt.pm * tstep : cA; const char* nB = has_next ? (const char*)g.Bt + (size_t)nxt.pn * tstep : cB;
;         for (int t = 0; t < nt; t += 2) {
;             const bool last = (t == nt - 2);
;             const char* a1 = cA + (size_t)(t + 1) * kstep;
;             const char* a2 = last ? nA : cA + (size_t)(t + 2) * kstep; const char* b2 = last ? nB : cB + (size_t)(t + 2) * kstep;
;             const char* a3 = a2 + kstep; const char* b3 = b2 + kstep;
;     ...
; #pragma unroll
;         for (int a = 0; a < 2; ++a)
; #pragma unroll
;             for (int b = 0; b < 2; ++b)
; #pragma unroll
;                 for (int m = 0; m < 4; ++m)
; #pragma unroll
;                     for (int n = 0; n < 2; ++n) acc[a][b][m][n] = (f32x4){0.f, 0.f, 0.f, 0.f};
.LBB0_993:
	s_add_u32 s36, s36, 0x160080
	s_addc_u32 s37, s37, 0
	s_add_u32 s61, s38, 0x100
	v_mov_b32_e32 v2, 0
	s_addc_u32 s62, s39, 0
	s_mov_b32 s63, -2
	v_mov_b32_e32 v3, v2
	v_mov_b64_e32 v[4:5], 0
	v_mov_b64_e32 v[6:7], 0
	v_mov_b64_e32 v[8:9], 0
	v_mov_b64_e32 v[18:19], 0
	v_mov_b64_e32 v[20:21], 0
	v_mov_b64_e32 v[22:23], 0
	s_waitcnt lgkmcnt(0)
	v_mov_b64_e32 v[24:25], 0
	v_mov_b64_e32 v[34:35], 0
	v_mov_b64_e32 v[36:37], 0
	v_mov_b64_e32 v[38:39], 0
	v_mov_b64_e32 v[40:41], 0
	v_mov_b64_e32 v[50:51], 0
	v_mov_b64_e32 v[52:53], 0
	v_mov_b64_e32 v[54:55], 0
	v_mov_b64_e32 v[56:57], 0
	v_mov_b64_e32 v[10:11], 0
	v_mov_b64_e32 v[12:13], 0
	v_mov_b64_e32 v[14:15], 0
	v_mov_b64_e32 v[16:17], 0
	v_mov_b64_e32 v[26:27], 0
	v_mov_b64_e32 v[28:29], 0
	v_mov_b64_e32 v[30:31], 0
	v_mov_b64_e32 v[32:33], 0
	v_mov_b64_e32 v[42:43], 0
	v_mov_b64_e32 v[44:45], 0
	v_mov_b64_e32 v[46:47], 0
	v_mov_b64_e32 v[48:49], 0
	v_mov_b64_e32 v[58:59], 0
	v_mov_b64_e32 v[60:61], 0
	v_mov_b64_e32 v[62:63], 0
	v_mov_b64_e32 v[64:65], 0
	v_mov_b64_e32 v[66:67], 0
	v_mov_b64_e32 v[68:69], 0
	v_mov_b64_e32 v[70:71], 0
	v_mov_b64_e32 v[72:73], 0
	v_mov_b64_e32 v[82:83], 0
	v_mov_b64_e32 v[84:85], 0
	v_mov_b64_e32 v[86:87], 0
	v_mov_b64_e32 v[88:89], 0
	v_mov_b64_e32 v[98:99], 0
	v_mov_b64_e32 v[100:101], 0
	v_mov_b64_e32 v[102:103], 0
	v_mov_b64_e32 v[104:105], 0
	v_mov_b64_e32 v[114:115], 0
	v_mov_b64_e32 v[116:117], 0
	v_mov_b64_e32 v[118:119], 0
	v_mov_b64_e32 v[120:121], 0
	v_mov_b64_e32 v[74:75], 0
	v_mov_b64_e32 v[76:77], 0
	v_mov_b64_e32 v[78:79], 0
	v_mov_b64_e32 v[80:81], 0
	v_mov_b64_e32 v[90:91], 0
	v_mov_b64_e32 v[92:93], 0
	v_mov_b64_e32 v[94:95], 0
	v_mov_b64_e32 v[96:97], 0
	v_mov_b64_e32 v[106:107], 0
	v_mov_b64_e32 v[108:109], 0
	v_mov_b64_e32 v[110:111], 0
	v_mov_b64_e32 v[112:113], 0
	v_mov_b64_e32 v[122:123], 0
	v_mov_b64_e32 v[124:125], 0
	v_mov_b64_e32 v[126:127], 0
	v_mov_b64_e32 v[128:129], 0
